# c12_stash_readback_prefetch
# speedup vs baseline: 1.0158x; 1.0158x over previous
.LBB0_1477:
	v_rcp_f32_e32 v113, v80
	v_rcp_f32_e32 v112, v81
	v_rcp_f32_e32 v111, v82
	v_rcp_f32_e32 v110, v83
	v_rcp_f32_e32 v109, v12
	v_rcp_f32_e32 v108, v13
	v_rcp_f32_e32 v107, v14
	v_rcp_f32_e32 v106, v15
	v_rcp_f32_e32 v105, v8
	v_rcp_f32_e32 v104, v9
	v_rcp_f32_e32 v103, v10
	v_rcp_f32_e32 v102, v11
	v_rcp_f32_e32 v101, v4
	v_rcp_f32_e32 v100, v5
	v_rcp_f32_e32 v99, v6
	v_rcp_f32_e32 v98, v7
	v_mov_b32_e32 v4, v203
	s_mov_b64 s[4:5], -1
	v_ashrrev_i32_e32 v5, 31, v4
	v_lshl_add_u64 v[0:1], v[4:5], 2, s[8:9]
	s_and_b64 vcc, exec, s[48:49]
	s_cbranch_vccz .LBB0_1479
	s_mov_b32 s4, 0x8000
	v_add_co_u32_e32 v6, vcc, s4, v0
	s_mov_b32 s4, 0x10000
	s_nop 0
	v_addc_co_u32_e32 v7, vcc, 0, v1, vcc
	v_add_co_u32_e32 v118, vcc, s74, v0
	global_load_dword v5, v[0:1], off
	s_nop 0
	v_addc_co_u32_e32 v119, vcc, 0, v1, vcc
	v_add_co_u32_e32 v8, vcc, s4, v0
	s_mov_b32 s4, 0x18000
	s_nop 0
	v_addc_co_u32_e32 v9, vcc, 0, v1, vcc
	v_add_co_u32_e32 v120, vcc, s73, v0
	global_load_dword v140, v[118:119], off offset:-4096
	s_nop 0
	v_addc_co_u32_e32 v121, vcc, 0, v1, vcc
	v_add_co_u32_e32 v10, vcc, s4, v0
	global_load_dword v130, v[120:121], off offset:-4096
	s_nop 0
	v_addc_co_u32_e32 v11, vcc, 0, v1, vcc
	v_add_co_u32_e32 v122, vcc, s72, v0
	s_movk_i32 s4, 0x1000
	s_nop 0
	v_addc_co_u32_e32 v123, vcc, 0, v1, vcc
	global_load_dword v114, v[122:123], off offset:-4096
	global_load_dword v115, v[10:11], off offset:2048
	global_load_dword v131, v[8:9], off offset:2048
	global_load_dword v142, v[6:7], off offset:2048
	s_nop 0
	global_load_dword v8, v[0:1], off offset:2048
	v_add_co_u32_e32 v124, vcc, s4, v0
	s_movk_i32 s4, 0x2000
	s_nop 0
	v_addc_co_u32_e32 v125, vcc, 0, v1, vcc
	v_add_co_u32_e32 v6, vcc, s4, v0
	global_load_dword v116, v[122:123], off
	global_load_dword v132, v[120:121], off
	global_load_dword v143, v[118:119], off
	v_addc_co_u32_e32 v7, vcc, 0, v1, vcc
	global_load_dword v9, v[6:7], off offset:-4096
	global_load_dword v117, v[122:123], off offset:2048
	global_load_dword v133, v[120:121], off offset:2048
	global_load_dword v146, v[118:119], off offset:2048
	global_load_dword v10, v[124:125], off offset:2048
	v_add_co_u32_e32 v120, vcc, s75, v0
	v_mul_f32_e64 v12, v112, -v204
	s_nop 0
	v_addc_co_u32_e32 v121, vcc, 0, v1, vcc
	v_add_co_u32_e32 v122, vcc, s84, v0
	v_mul_f32_e64 v14, v109, -v204
	s_nop 0
	v_addc_co_u32_e32 v123, vcc, 0, v1, vcc
	v_add_co_u32_e32 v124, vcc, s76, v0
	s_movk_i32 s4, 0x4000
	s_nop 0
	v_addc_co_u32_e32 v125, vcc, 0, v1, vcc
	v_add_co_u32_e32 v126, vcc, s79, v0
	v_mul_f32_e64 v80, v108, -v204
	s_nop 0
	v_addc_co_u32_e32 v127, vcc, 0, v1, vcc
	v_add_co_u32_e32 v138, vcc, s77, v0
	v_mul_f32_e64 v82, v107, -v204
	s_nop 0
	v_addc_co_u32_e32 v139, vcc, 0, v1, vcc
	v_add_co_u32_e32 v144, vcc, s78, v0
	v_mul_f32_e64 v84, v106, -v204
	s_nop 0
	v_addc_co_u32_e32 v145, vcc, 0, v1, vcc
	v_mul_f32_e64 v86, v105, -v204
	v_mul_f32_e64 v88, v104, -v204
	v_mul_f32_e64 v90, v103, -v204
	v_mul_f32_e64 v92, v102, -v204
	v_mul_f32_e64 v94, v101, -v204
	v_mul_f32_e64 v96, v100, -v204
	v_mul_f32_e64 v129, v99, -v204
	v_mul_f32_e64 v2, v113, -v204
	v_mul_f32_e64 v134, v98, -v204
	v_mul_f32_e64 v15, v111, -v204
	v_mul_f32_e64 v83, v110, -v204
	global_load_dword v155, v[122:123], off offset:-4096
	global_load_dword v136, v[126:127], off offset:-4096
	global_load_dword v119, v[144:145], off offset:-4096
	v_lshlrev_b32_e32 v245, 2, v203
	s_add_u32 s98, s8, 0x3000
	s_addc_u32 s99, s9, 0
	global_load_dword v184, v245, s[98:99] offset:-4096
	global_load_dword v190, v245, s[98:99] offset:-2048
	global_load_dword v194, v245, s[98:99]
	global_load_dword v212, v245, s[98:99] offset:2048
	s_add_u32 s98, s8, 0x5000
	s_addc_u32 s99, s9, 0
	global_load_dword v215, v245, s[98:99] offset:-4096
	global_load_dword v220, v245, s[98:99] offset:-2048
	global_load_dword v224, v245, s[98:99]
	global_load_dword v229, v245, s[98:99] offset:2048
	s_add_u32 s98, s8, 0x7000
	s_addc_u32 s99, s9, 0
	global_load_dword v233, v245, s[98:99] offset:-4096
	global_load_dword v237, v245, s[98:99] offset:-2048
	global_load_dword v241, v245, s[98:99]
	global_load_dword v247, v245, s[98:99] offset:2048
	s_add_u32 s98, s8, 0xb000
	s_addc_u32 s99, s9, 0
	global_load_dword v189, v245, s[98:99] offset:-2048
	global_load_dword v193, v245, s[98:99]
	global_load_dword v197, v245, s[98:99] offset:2048
	s_add_u32 s98, s8, 0xd000
	s_addc_u32 s99, s9, 0
	global_load_dword v213, v245, s[98:99] offset:-4096
	global_load_dword v219, v245, s[98:99] offset:-2048
	global_load_dword v223, v245, s[98:99]
	global_load_dword v227, v245, s[98:99] offset:2048
	s_add_u32 s98, s8, 0xf000
	s_addc_u32 s99, s9, 0
	global_load_dword v230, v245, s[98:99] offset:-4096
	global_load_dword v236, v245, s[98:99] offset:-2048
	global_load_dword v240, v245, s[98:99]
	global_load_dword v246, v245, s[98:99] offset:2048
	s_add_u32 s98, s8, 0x13000
	s_addc_u32 s99, s9, 0
	global_load_dword v188, v245, s[98:99] offset:-2048
	global_load_dword v192, v245, s[98:99]
	global_load_dword v196, v245, s[98:99] offset:2048
	s_add_u32 s98, s8, 0x15000
	s_addc_u32 s99, s9, 0
	global_load_dword v214, v245, s[98:99] offset:-4096
	global_load_dword v218, v245, s[98:99] offset:-2048
	global_load_dword v222, v245, s[98:99]
	global_load_dword v226, v245, s[98:99] offset:2048
	s_add_u32 s98, s8, 0x17000
	s_addc_u32 s99, s9, 0
	global_load_dword v231, v245, s[98:99] offset:-4096
	global_load_dword v235, v245, s[98:99] offset:-2048
	global_load_dword v239, v245, s[98:99]
	global_load_dword v243, v245, s[98:99] offset:2048
	s_add_u32 s98, s8, 0x1b000
	s_addc_u32 s99, s9, 0
	global_load_dword v185, v245, s[98:99] offset:-2048
	global_load_dword v191, v245, s[98:99]
	global_load_dword v195, v245, s[98:99] offset:2048
	s_add_u32 s98, s8, 0x1d000
	s_addc_u32 s99, s9, 0
	global_load_dword v216, v245, s[98:99] offset:-4096
	global_load_dword v217, v245, s[98:99] offset:-2048
	global_load_dword v221, v245, s[98:99]
	global_load_dword v225, v245, s[98:99] offset:2048
	s_add_u32 s98, s8, 0x1f000
	s_addc_u32 s99, s9, 0
	global_load_dword v232, v245, s[98:99] offset:-4096
	global_load_dword v234, v245, s[98:99] offset:-2048
	global_load_dword v238, v245, s[98:99]
	global_load_dword v242, v245, s[98:99] offset:2048
	s_waitcnt vmcnt(0)
	v_fmac_f32_e32 v5, v2, v64
	v_fmac_f32_e32 v140, v2, v48
	v_mul_f32_e32 v13, v140, v140
	v_fmac_f32_e32 v13, v5, v5
	v_fmac_f32_e32 v130, v2, v32
	v_fmac_f32_e32 v13, v130, v130
	v_fmac_f32_e32 v115, v12, v17
	v_fmac_f32_e32 v131, v12, v33
	v_fmac_f32_e32 v142, v12, v49
	v_fmac_f32_e32 v8, v12, v65
	v_mov_b32_e32 v12, v184
	v_fmac_f32_e32 v114, v2, v16
	v_fmac_f32_e32 v13, v114, v114
	v_mul_f32_e32 v11, v142, v142
	v_fmac_f32_e32 v11, v8, v8
	v_fmac_f32_e32 v11, v131, v131
	v_fmac_f32_e32 v11, v115, v115
	v_fmac_f32_e32 v143, v15, v50
	v_mul_f32_e32 v2, v143, v143
	v_fmac_f32_e32 v132, v15, v34
	v_fmac_f32_e32 v9, v15, v66
	v_fmac_f32_e32 v2, v9, v9
	v_fmac_f32_e32 v2, v132, v132
	v_fmac_f32_e32 v116, v15, v18
	v_fmac_f32_e32 v2, v116, v116
	v_fmac_f32_e32 v146, v83, v51
	v_fmac_f32_e32 v10, v83, v67
	v_mul_f32_e32 v81, v146, v146
	v_fmac_f32_e32 v81, v10, v10
	v_fmac_f32_e32 v133, v83, v35
	v_fmac_f32_e32 v81, v133, v133
	v_fmac_f32_e32 v117, v83, v19
	v_fmac_f32_e32 v81, v117, v117
	v_fmac_f32_e32 v155, v14, v52
	v_fmac_f32_e32 v136, v14, v36
	v_fmac_f32_e32 v119, v14, v20
	v_mul_f32_e32 v83, v155, v155
	s_waitcnt vmcnt(0)
	v_fmac_f32_e32 v12, v14, v68
	v_mov_b32_e32 v118, v185
	s_nop 0
	v_mov_b32_e32 v138, v188
	v_mov_b32_e32 v157, v189
	v_mov_b32_e32 v14, v190
	v_add_co_u32_e32 v6, vcc, s85, v0
	v_mov_b32_e32 v120, v191
	v_mov_b32_e32 v139, v192
	v_mov_b32_e32 v158, v193
	v_addc_co_u32_e32 v7, vcc, 0, v1, vcc
	v_add_co_u32_e32 v124, vcc, s4, v0
	s_mov_b32 s4, 0xc000
	s_nop 0
	v_addc_co_u32_e32 v125, vcc, 0, v1, vcc
	v_fmac_f32_e32 v83, v12, v12
	v_fmac_f32_e32 v83, v136, v136
	v_fmac_f32_e32 v83, v119, v119
	s_waitcnt vmcnt(0)
	v_fmac_f32_e32 v118, v80, v21
	v_fmac_f32_e32 v138, v80, v37
	v_fmac_f32_e32 v157, v80, v53
	v_fmac_f32_e32 v14, v80, v69
	v_mov_b32_e32 v80, v194
	v_fmac_f32_e32 v139, v82, v38
	v_fmac_f32_e32 v158, v82, v54
	v_fmac_f32_e32 v120, v82, v22
	v_mul_f32_e32 v15, v157, v157
	v_fmac_f32_e32 v15, v14, v14
	v_fmac_f32_e32 v15, v138, v138
	v_fmac_f32_e32 v15, v118, v118
	v_mul_f32_e32 v85, v158, v158
	s_waitcnt vmcnt(0)
	v_fmac_f32_e32 v80, v82, v70
	v_mov_b32_e32 v121, v195
	s_nop 0
	v_mov_b32_e32 v145, v196
	v_mov_b32_e32 v166, v197
	v_mov_b32_e32 v82, v212
	v_add_co_u32_e32 v6, vcc, s4, v0
	s_movk_i32 s4, 0x6000
	s_nop 0
	v_addc_co_u32_e32 v7, vcc, 0, v1, vcc
	v_add_co_u32_e32 v126, vcc, s90, v0
	v_fmac_f32_e32 v85, v80, v80
	s_nop 0
	v_addc_co_u32_e32 v127, vcc, 0, v1, vcc
	v_add_co_u32_e32 v150, vcc, s86, v0
	v_fmac_f32_e32 v85, v139, v139
	s_nop 0
	v_addc_co_u32_e32 v151, vcc, 0, v1, vcc
	v_add_co_u32_e32 v160, vcc, s89, v0
	v_fmac_f32_e32 v85, v120, v120
	s_nop 0
	v_addc_co_u32_e32 v161, vcc, 0, v1, vcc
	v_add_co_u32_e32 v152, vcc, s87, v0
	v_mov_b32_e32 v170, v213
	v_mov_b32_e32 v149, v214
	v_addc_co_u32_e32 v153, vcc, 0, v1, vcc
	v_add_co_u32_e32 v162, vcc, s88, v0
	s_waitcnt vmcnt(0)
	v_fmac_f32_e32 v121, v84, v23
	v_addc_co_u32_e32 v163, vcc, 0, v1, vcc
	v_fmac_f32_e32 v82, v84, v71
	v_fmac_f32_e32 v166, v84, v55
	v_fmac_f32_e32 v145, v84, v39
	v_mov_b32_e32 v84, v215
	v_mov_b32_e32 v123, v216
	v_add_co_u32_e32 v164, vcc, s91, v0
	v_mul_f32_e32 v89, v166, v166
	s_nop 0
	v_addc_co_u32_e32 v165, vcc, 0, v1, vcc
	v_fmac_f32_e32 v89, v82, v82
	v_fmac_f32_e32 v89, v145, v145
	v_fmac_f32_e32 v89, v121, v121
	v_fmac_f32_e32 v170, v86, v56
	v_fmac_f32_e32 v149, v86, v40
	v_mul_f32_e32 v93, v170, v170
	s_waitcnt vmcnt(0)
	v_fmac_f32_e32 v84, v86, v72
	v_fmac_f32_e32 v123, v86, v24
	v_mov_b32_e32 v122, v217
	s_nop 0
	v_mov_b32_e32 v151, v218
	s_nop 0
	v_mov_b32_e32 v171, v219
	v_mov_b32_e32 v86, v220
	v_add_co_u32_e32 v6, vcc, s4, v0
	v_mov_b32_e32 v124, v221
	v_mov_b32_e32 v152, v222
	v_mov_b32_e32 v172, v223
	v_addc_co_u32_e32 v7, vcc, 0, v1, vcc
	s_mov_b32 s4, 0x1f000
	v_fmac_f32_e32 v93, v84, v84
	v_fmac_f32_e32 v93, v149, v149
	v_fmac_f32_e32 v93, v123, v123
	s_waitcnt vmcnt(0)
	v_fmac_f32_e32 v122, v88, v25
	v_fmac_f32_e32 v151, v88, v41
	v_fmac_f32_e32 v171, v88, v57
	v_fmac_f32_e32 v86, v88, v73
	v_mov_b32_e32 v88, v224
	v_fmac_f32_e32 v152, v90, v42
	v_fmac_f32_e32 v172, v90, v58
	v_fmac_f32_e32 v124, v90, v26
	v_mul_f32_e32 v87, v171, v171
	v_fmac_f32_e32 v87, v86, v86
	v_fmac_f32_e32 v87, v151, v151
	v_fmac_f32_e32 v87, v122, v122
	v_mul_f32_e32 v91, v172, v172
	s_waitcnt vmcnt(0)
	v_fmac_f32_e32 v88, v90, v74
	v_mov_b32_e32 v125, v225
	v_mov_b32_e32 v154, v226
	v_mov_b32_e32 v173, v227
	v_mov_b32_e32 v90, v229
	v_add_co_u32_e32 v160, vcc, s92, v0
	v_fmac_f32_e32 v91, v88, v88
	s_nop 0
	v_addc_co_u32_e32 v161, vcc, 0, v1, vcc
	v_add_co_u32_e32 v162, vcc, s96, v0
	v_fmac_f32_e32 v91, v152, v152
	s_nop 0
	v_addc_co_u32_e32 v163, vcc, 0, v1, vcc
	v_add_co_u32_e32 v168, vcc, s93, v0
	v_fmac_f32_e32 v91, v124, v124
	s_nop 0
	v_addc_co_u32_e32 v169, vcc, 0, v1, vcc
	v_add_co_u32_e32 v178, vcc, s95, v0
	v_mov_b32_e32 v174, v230
	s_nop 0
	v_addc_co_u32_e32 v179, vcc, 0, v1, vcc
	v_add_co_u32_e32 v176, vcc, s94, v0
	v_mov_b32_e32 v164, v231
	s_nop 0
	v_addc_co_u32_e32 v177, vcc, 0, v1, vcc
	v_add_co_u32_e32 v180, vcc, s4, v0
	s_mov_b64 s[4:5], 0x80
	s_nop 0
	v_addc_co_u32_e32 v181, vcc, 0, v1, vcc
	v_mov_b32_e32 v127, v232
	s_waitcnt vmcnt(0)
	v_fmac_f32_e32 v125, v92, v27
	v_fmac_f32_e32 v154, v92, v43
	v_fmac_f32_e32 v173, v92, v59
	v_fmac_f32_e32 v90, v92, v75
	v_mov_b32_e32 v92, v233
	v_mul_f32_e32 v95, v173, v173
	v_fmac_f32_e32 v95, v90, v90
	v_fmac_f32_e32 v95, v154, v154
	v_fmac_f32_e32 v95, v125, v125
	v_fmac_f32_e32 v174, v94, v60
	v_mul_f32_e32 v97, v174, v174
	v_fmac_f32_e32 v164, v94, v44
	v_fmac_f32_e32 v127, v94, v28
	s_waitcnt vmcnt(0)
	v_fmac_f32_e32 v92, v94, v76
	v_mov_b32_e32 v126, v234
	v_mov_b32_e32 v167, v235
	v_mov_b32_e32 v175, v236
	v_mov_b32_e32 v94, v237
	v_add_co_u32_e32 v160, vcc, s97, v0
	v_mov_b32_e32 v128, v238
	v_mov_b32_e32 v168, v239
	v_mov_b32_e32 v176, v240
	v_addc_co_u32_e32 v161, vcc, 0, v1, vcc
	v_fmac_f32_e32 v97, v92, v92
	v_fmac_f32_e32 v97, v164, v164
	v_fmac_f32_e32 v97, v127, v127
	s_waitcnt vmcnt(0)
	v_fmac_f32_e32 v126, v96, v29
	v_fmac_f32_e32 v167, v96, v45
	v_fmac_f32_e32 v175, v96, v61
	v_fmac_f32_e32 v94, v96, v77
	v_mov_b32_e32 v96, v241
	v_fmac_f32_e32 v168, v129, v46
	v_fmac_f32_e32 v176, v129, v62
	v_fmac_f32_e32 v128, v129, v30
	v_mul_f32_e32 v6, v175, v175
	v_fmac_f32_e32 v6, v94, v94
	v_fmac_f32_e32 v6, v167, v167
	v_fmac_f32_e32 v6, v126, v126
	v_mul_f32_e32 v7, v176, v176
	s_waitcnt vmcnt(0)
	v_fmac_f32_e32 v96, v129, v78
	v_mov_b32_e32 v129, v242
	v_mov_b32_e32 v169, v243
	v_mov_b32_e32 v177, v246
	s_nop 0
	v_mov_b32_e32 v178, v247
	v_fmac_f32_e32 v7, v96, v96
	v_fmac_f32_e32 v7, v168, v168
	v_fmac_f32_e32 v7, v128, v128
	s_waitcnt vmcnt(0)
	v_fmac_f32_e32 v129, v134, v31
	v_fmac_f32_e32 v169, v134, v47
	v_fmac_f32_e32 v177, v134, v63
	v_fmac_f32_e32 v178, v134, v79
	ds_bpermute_b32 v134, v198, v13
	v_mul_f32_e32 v165, v177, v177
	v_fmac_f32_e32 v165, v178, v178
	v_fmac_f32_e32 v165, v169, v169
	v_fmac_f32_e32 v165, v129, v129
	s_waitcnt lgkmcnt(0)
	v_add_f32_e32 v13, v13, v134
	ds_bpermute_b32 v134, v199, v13
	s_waitcnt lgkmcnt(0)
	v_add_f32_e32 v13, v13, v134
	ds_bpermute_b32 v134, v200, v13
	s_waitcnt lgkmcnt(0)
	v_add_f32_e32 v13, v13, v134
	ds_bpermute_b32 v134, v201, v13
	s_waitcnt lgkmcnt(0)
	v_add_f32_e32 v13, v13, v134
	ds_bpermute_b32 v134, v202, v13
	s_waitcnt lgkmcnt(0)
	v_add_f32_e32 v13, v13, v134
	v_fmamk_f32 v13, v13, 0x3c000000, v206
	v_rsq_f32_e32 v13, v13
	s_nop 0
	v_mul_f32_e32 v134, 0x3f24fd5c, v13
	ds_bpermute_b32 v13, v198, v11
	v_mul_f32_e32 v140, v134, v140
	v_mul_f32_e32 v130, v134, v130
	v_mul_f32_e32 v114, v134, v114
	s_waitcnt lgkmcnt(0)
	v_add_f32_e32 v11, v11, v13
	ds_bpermute_b32 v13, v199, v11
	s_waitcnt lgkmcnt(0)
	v_add_f32_e32 v11, v11, v13
	ds_bpermute_b32 v13, v200, v11
	s_waitcnt lgkmcnt(0)
	v_add_f32_e32 v11, v11, v13
	ds_bpermute_b32 v13, v201, v11
	s_waitcnt lgkmcnt(0)
	v_add_f32_e32 v11, v11, v13
	ds_bpermute_b32 v13, v202, v11
	s_waitcnt lgkmcnt(0)
	v_add_f32_e32 v11, v11, v13
	v_fmamk_f32 v11, v11, 0x3c000000, v206
	v_rsq_f32_e32 v11, v11
	s_nop 0
	v_mul_f32_e32 v135, 0x3f24fd5c, v11
	ds_bpermute_b32 v11, v198, v2
	v_mul_f32_e32 v8, v135, v8
	s_waitcnt lgkmcnt(0)
	v_add_f32_e32 v2, v2, v11
	ds_bpermute_b32 v11, v199, v2
	s_waitcnt lgkmcnt(0)
	v_add_f32_e32 v2, v2, v11
	ds_bpermute_b32 v11, v200, v2
	s_waitcnt lgkmcnt(0)
	v_add_f32_e32 v2, v2, v11
	ds_bpermute_b32 v11, v201, v2
	s_waitcnt lgkmcnt(0)
	v_add_f32_e32 v2, v2, v11
	ds_bpermute_b32 v11, v202, v2
	s_waitcnt lgkmcnt(0)
	v_add_f32_e32 v2, v2, v11
	v_fmamk_f32 v2, v2, 0x3c000000, v206
	v_rsq_f32_e32 v2, v2
	s_nop 0
	v_mul_f32_e32 v137, 0x3f24fd5c, v2
	ds_bpermute_b32 v2, v198, v81
	s_waitcnt lgkmcnt(0)
	v_add_f32_e32 v2, v81, v2
	ds_bpermute_b32 v11, v199, v2
	s_waitcnt lgkmcnt(0)
	v_add_f32_e32 v2, v2, v11
	ds_bpermute_b32 v11, v200, v2
	s_waitcnt lgkmcnt(0)
	v_add_f32_e32 v2, v2, v11
	ds_bpermute_b32 v11, v201, v2
	s_waitcnt lgkmcnt(0)
	v_add_f32_e32 v2, v2, v11
	ds_bpermute_b32 v11, v202, v2
	s_waitcnt lgkmcnt(0)
	v_add_f32_e32 v2, v2, v11
	v_fmamk_f32 v2, v2, 0x3c000000, v206
	v_rsq_f32_e32 v2, v2
	s_nop 0
	v_mul_f32_e32 v141, 0x3f24fd5c, v2
	ds_bpermute_b32 v2, v198, v83
	v_mul_f32_e32 v10, v141, v10
	s_waitcnt lgkmcnt(0)
	v_add_f32_e32 v2, v83, v2
	ds_bpermute_b32 v11, v199, v2
	s_waitcnt lgkmcnt(0)
	v_add_f32_e32 v2, v2, v11
	ds_bpermute_b32 v11, v200, v2
	s_waitcnt lgkmcnt(0)
	v_add_f32_e32 v2, v2, v11
	ds_bpermute_b32 v11, v201, v2
	s_waitcnt lgkmcnt(0)
	v_add_f32_e32 v2, v2, v11
	ds_bpermute_b32 v11, v202, v2
	s_waitcnt lgkmcnt(0)
	v_add_f32_e32 v2, v2, v11
	v_fmamk_f32 v2, v2, 0x3c000000, v206
	v_rsq_f32_e32 v2, v2
	s_nop 0
	v_mul_f32_e32 v144, 0x3f24fd5c, v2
	ds_bpermute_b32 v2, v198, v15
	v_mul_f32_e32 v12, v144, v12
	s_waitcnt lgkmcnt(0)
	v_add_f32_e32 v2, v15, v2
	ds_bpermute_b32 v11, v199, v2
	s_waitcnt lgkmcnt(0)
	v_add_f32_e32 v2, v2, v11
	ds_bpermute_b32 v11, v200, v2
	s_waitcnt lgkmcnt(0)
	v_add_f32_e32 v2, v2, v11
	ds_bpermute_b32 v11, v201, v2
	s_waitcnt lgkmcnt(0)
	v_add_f32_e32 v2, v2, v11
	ds_bpermute_b32 v11, v202, v2
	s_waitcnt lgkmcnt(0)
	v_add_f32_e32 v2, v2, v11
	v_fmamk_f32 v2, v2, 0x3c000000, v206
	v_rsq_f32_e32 v2, v2
	s_nop 0
	v_mul_f32_e32 v147, 0x3f24fd5c, v2
	ds_bpermute_b32 v2, v198, v85
	v_mul_f32_e32 v14, v147, v14
	s_waitcnt lgkmcnt(0)
	v_add_f32_e32 v2, v85, v2
	ds_bpermute_b32 v11, v199, v2
	s_waitcnt lgkmcnt(0)
	v_add_f32_e32 v2, v2, v11
	ds_bpermute_b32 v11, v200, v2
	s_waitcnt lgkmcnt(0)
	v_add_f32_e32 v2, v2, v11
	ds_bpermute_b32 v11, v201, v2
	s_waitcnt lgkmcnt(0)
	v_add_f32_e32 v2, v2, v11
	ds_bpermute_b32 v11, v202, v2
	s_waitcnt lgkmcnt(0)
	v_add_f32_e32 v2, v2, v11
	v_fmamk_f32 v2, v2, 0x3c000000, v206
	v_rsq_f32_e32 v2, v2
	s_nop 0
	v_mul_f32_e32 v148, 0x3f24fd5c, v2
	ds_bpermute_b32 v2, v198, v89
	v_mul_f32_e32 v80, v148, v80
	s_waitcnt lgkmcnt(0)
	v_add_f32_e32 v2, v89, v2
	ds_bpermute_b32 v11, v199, v2
	s_waitcnt lgkmcnt(0)
	v_add_f32_e32 v2, v2, v11
	ds_bpermute_b32 v11, v200, v2
	s_waitcnt lgkmcnt(0)
	v_add_f32_e32 v2, v2, v11
	ds_bpermute_b32 v11, v201, v2
	s_waitcnt lgkmcnt(0)
	v_add_f32_e32 v2, v2, v11
	ds_bpermute_b32 v11, v202, v2
	s_waitcnt lgkmcnt(0)
	v_add_f32_e32 v2, v2, v11
	v_fmamk_f32 v2, v2, 0x3c000000, v206
	v_rsq_f32_e32 v2, v2
	s_nop 0
	v_mul_f32_e32 v150, 0x3f24fd5c, v2
	ds_bpermute_b32 v2, v198, v93
	v_mul_f32_e32 v82, v150, v82
	s_waitcnt lgkmcnt(0)
	v_add_f32_e32 v2, v93, v2
	ds_bpermute_b32 v11, v199, v2
	s_waitcnt lgkmcnt(0)
	v_add_f32_e32 v2, v2, v11
	ds_bpermute_b32 v11, v200, v2
	s_waitcnt lgkmcnt(0)
	v_add_f32_e32 v2, v2, v11
	ds_bpermute_b32 v11, v201, v2
	s_waitcnt lgkmcnt(0)
	v_add_f32_e32 v2, v2, v11
	ds_bpermute_b32 v11, v202, v2
	s_waitcnt lgkmcnt(0)
	v_add_f32_e32 v2, v2, v11
	v_fmamk_f32 v2, v2, 0x3c000000, v206
	v_rsq_f32_e32 v2, v2
	s_nop 0
	v_mul_f32_e32 v153, 0x3f24fd5c, v2
	ds_bpermute_b32 v2, v198, v87
	v_mul_f32_e32 v84, v153, v84
	s_waitcnt lgkmcnt(0)
	v_add_f32_e32 v2, v87, v2
	ds_bpermute_b32 v11, v199, v2
	s_waitcnt lgkmcnt(0)
	v_add_f32_e32 v2, v2, v11
	ds_bpermute_b32 v11, v200, v2
	s_waitcnt lgkmcnt(0)
	v_add_f32_e32 v2, v2, v11
	ds_bpermute_b32 v11, v201, v2
	s_waitcnt lgkmcnt(0)
	v_add_f32_e32 v2, v2, v11
	ds_bpermute_b32 v11, v202, v2
	s_waitcnt lgkmcnt(0)
	v_add_f32_e32 v2, v2, v11
	v_fmamk_f32 v2, v2, 0x3c000000, v206
	v_rsq_f32_e32 v2, v2
	s_nop 0
	v_mul_f32_e32 v156, 0x3f24fd5c, v2
	ds_bpermute_b32 v2, v198, v91
	v_mul_f32_e32 v86, v156, v86
	s_waitcnt lgkmcnt(0)
	v_add_f32_e32 v2, v91, v2
	ds_bpermute_b32 v11, v199, v2
	s_waitcnt lgkmcnt(0)
	v_add_f32_e32 v2, v2, v11
	ds_bpermute_b32 v11, v200, v2
	s_waitcnt lgkmcnt(0)
	v_add_f32_e32 v2, v2, v11
	ds_bpermute_b32 v11, v201, v2
	s_waitcnt lgkmcnt(0)
	v_add_f32_e32 v2, v2, v11
	ds_bpermute_b32 v11, v202, v2
	s_waitcnt lgkmcnt(0)
	v_add_f32_e32 v2, v2, v11
	v_fmamk_f32 v2, v2, 0x3c000000, v206
	v_rsq_f32_e32 v2, v2
	s_nop 0
	v_mul_f32_e32 v159, 0x3f24fd5c, v2
	ds_bpermute_b32 v2, v198, v95
	v_mul_f32_e32 v88, v159, v88
	s_waitcnt lgkmcnt(0)
	v_add_f32_e32 v2, v95, v2
	ds_bpermute_b32 v11, v199, v2
	s_waitcnt lgkmcnt(0)
	v_add_f32_e32 v2, v2, v11
	ds_bpermute_b32 v11, v200, v2
	s_waitcnt lgkmcnt(0)
	v_add_f32_e32 v2, v2, v11
	ds_bpermute_b32 v11, v201, v2
	s_waitcnt lgkmcnt(0)
	v_add_f32_e32 v2, v2, v11
	ds_bpermute_b32 v11, v202, v2
	s_waitcnt lgkmcnt(0)
	v_add_f32_e32 v2, v2, v11
	v_fmamk_f32 v2, v2, 0x3c000000, v206
	v_rsq_f32_e32 v2, v2
	s_nop 0
	v_mul_f32_e32 v160, 0x3f24fd5c, v2
	ds_bpermute_b32 v2, v198, v97
	v_mul_f32_e32 v90, v160, v90
	s_waitcnt lgkmcnt(0)
	v_add_f32_e32 v2, v97, v2
	ds_bpermute_b32 v11, v199, v2
	s_waitcnt lgkmcnt(0)
	v_add_f32_e32 v2, v2, v11
	ds_bpermute_b32 v11, v200, v2
	s_waitcnt lgkmcnt(0)
	v_add_f32_e32 v2, v2, v11
	ds_bpermute_b32 v11, v201, v2
	s_waitcnt lgkmcnt(0)
	v_add_f32_e32 v2, v2, v11
	ds_bpermute_b32 v11, v202, v2
	s_waitcnt lgkmcnt(0)
	v_add_f32_e32 v2, v2, v11
	v_fmamk_f32 v2, v2, 0x3c000000, v206
	v_rsq_f32_e32 v2, v2
	v_and_b32_e32 v11, 31, v4
	v_lshlrev_b32_e32 v179, 2, v11
	global_load_dword v182, v179, s[6:7]
	v_mul_f32_e32 v161, 0x3f24fd5c, v2
	ds_bpermute_b32 v2, v198, v6
	v_mul_f32_e32 v92, v161, v92
	s_waitcnt lgkmcnt(0)
	v_add_f32_e32 v2, v6, v2
	ds_bpermute_b32 v6, v199, v2
	s_waitcnt lgkmcnt(0)
	v_add_f32_e32 v2, v2, v6
	ds_bpermute_b32 v6, v200, v2
	s_waitcnt lgkmcnt(0)
	v_add_f32_e32 v2, v2, v6
	ds_bpermute_b32 v6, v201, v2
	s_waitcnt lgkmcnt(0)
	v_add_f32_e32 v2, v2, v6
	ds_bpermute_b32 v6, v202, v2
	s_waitcnt lgkmcnt(0)
	v_add_f32_e32 v2, v2, v6
	v_fmamk_f32 v2, v2, 0x3c000000, v206
	v_rsq_f32_e32 v2, v2
	s_waitcnt vmcnt(0)
	v_mul_f32_e32 v8, v182, v8
	v_mul_f32_e32 v162, 0x3f24fd5c, v2
	ds_bpermute_b32 v2, v198, v7
	v_mul_f32_e32 v10, v182, v10
	v_mul_f32_e32 v12, v182, v12
	v_mul_f32_e32 v14, v182, v14
	v_mul_f32_e32 v80, v182, v80
	s_waitcnt lgkmcnt(0)
	v_add_f32_e32 v2, v7, v2
	ds_bpermute_b32 v6, v199, v2
	v_mul_f32_e32 v82, v182, v82
	v_mul_f32_e32 v84, v182, v84
	v_mul_f32_e32 v86, v182, v86
	v_mul_f32_e32 v88, v182, v88
	s_waitcnt lgkmcnt(0)
	v_add_f32_e32 v2, v2, v6
	ds_bpermute_b32 v6, v200, v2
	v_mul_f32_e32 v90, v182, v90
	v_mul_f32_e32 v92, v182, v92
	v_mul_f32_e32 v94, v162, v94
	v_mul_f32_e32 v94, v182, v94
	s_waitcnt lgkmcnt(0)
	v_add_f32_e32 v2, v2, v6
	ds_bpermute_b32 v6, v201, v2
	s_waitcnt lgkmcnt(0)
	v_add_f32_e32 v2, v2, v6
	ds_bpermute_b32 v6, v202, v2
	s_waitcnt lgkmcnt(0)
	v_add_f32_e32 v2, v2, v6
	v_fmamk_f32 v2, v2, 0x3c000000, v206
	v_rsq_f32_e32 v2, v2
	s_nop 0
	v_mul_f32_e32 v163, 0x3f24fd5c, v2
	ds_bpermute_b32 v2, v198, v165
	v_mul_f32_e32 v96, v163, v96
	v_mul_f32_e32 v96, v182, v96
	s_waitcnt lgkmcnt(0)
	v_add_f32_e32 v2, v165, v2
	ds_bpermute_b32 v6, v199, v2
	s_waitcnt lgkmcnt(0)
	v_add_f32_e32 v2, v2, v6
	ds_bpermute_b32 v6, v200, v2
	s_waitcnt lgkmcnt(0)
	v_add_f32_e32 v2, v2, v6
	ds_bpermute_b32 v6, v201, v2
	s_waitcnt lgkmcnt(0)
	v_add_f32_e32 v2, v2, v6
	ds_bpermute_b32 v6, v202, v2
	s_waitcnt lgkmcnt(0)
	v_add_f32_e32 v2, v2, v6
	v_fmamk_f32 v2, v2, 0x3c000000, v206
	v_rsq_f32_e32 v2, v2
	s_nop 0
	v_mul_f32_e32 v165, 0x3f24fd5c, v2
	v_lshlrev_b32_e32 v2, 1, v11
	v_lshl_add_u64 v[6:7], s[46:47], 0, v[2:3]
	v_mul_f32_e32 v2, v134, v5
	v_mul_f32_e32 v2, v182, v2
	v_bfe_u32 v5, v2, 16, 1
	v_add3_u32 v11, v2, v5, s30
	v_lshlrev_b32_e32 v2, 8, v4
	v_and_b32_e32 v2, 0x2000, v2
	v_lshl_add_u64 v[4:5], v[6:7], 0, v[2:3]
	global_store_short_d16_hi v[4:5], v11, off
	v_bfe_u32 v11, v8, 16, 1
	v_add3_u32 v8, v8, v11, s30
	global_store_short_d16_hi v[4:5], v8, off offset:2048
	v_mul_f32_e32 v8, v137, v9
	v_mul_f32_e32 v8, v182, v8
	v_bfe_u32 v9, v8, 16, 1
	v_add3_u32 v11, v8, v9, s30
	v_or_b32_e32 v8, 0x1000, v2
	v_mov_b32_e32 v9, v3
	v_lshl_add_u64 v[180:181], v[6:7], 0, v[8:9]
	global_store_short_d16_hi v[180:181], v11, off
	v_bfe_u32 v11, v10, 16, 1
	v_add3_u32 v13, v10, v11, s30
	v_or_b32_e32 v10, 0x1800, v2
	v_mov_b32_e32 v11, v3
	v_lshl_add_u64 v[180:181], v[6:7], 0, v[10:11]
	global_store_short_d16_hi v[180:181], v13, off
	v_bfe_u32 v13, v12, 16, 1
	v_add3_u32 v15, v12, v13, s30
	v_or_b32_e32 v12, 0x4000, v2
	v_mov_b32_e32 v13, v3
	v_lshl_add_u64 v[180:181], v[6:7], 0, v[12:13]
	global_store_short_d16_hi v[180:181], v15, off
	v_bfe_u32 v15, v14, 16, 1
	v_add3_u32 v81, v14, v15, s30
	v_or_b32_e32 v14, 0x4800, v2
	v_mov_b32_e32 v15, v3
	v_lshl_add_u64 v[180:181], v[6:7], 0, v[14:15]
	global_store_short_d16_hi v[180:181], v81, off
	v_bfe_u32 v81, v80, 16, 1
	v_add3_u32 v83, v80, v81, s30
	v_or_b32_e32 v80, 0x5000, v2
	v_mov_b32_e32 v81, v3
	v_lshl_add_u64 v[180:181], v[6:7], 0, v[80:81]
	global_store_short_d16_hi v[180:181], v83, off
	v_bfe_u32 v83, v82, 16, 1
	v_add3_u32 v85, v82, v83, s30
	v_or_b32_e32 v82, 0x5800, v2
	v_mov_b32_e32 v83, v3
	v_lshl_add_u64 v[180:181], v[6:7], 0, v[82:83]
	global_store_short_d16_hi v[180:181], v85, off
	v_bfe_u32 v85, v84, 16, 1
	v_add3_u32 v87, v84, v85, s30
	v_or_b32_e32 v84, 0x8000, v2
	v_mov_b32_e32 v85, v3
	v_lshl_add_u64 v[180:181], v[6:7], 0, v[84:85]
	global_store_short_d16_hi v[180:181], v87, off
	v_bfe_u32 v87, v86, 16, 1
	v_add3_u32 v89, v86, v87, s30
	v_or_b32_e32 v86, 0x8800, v2
	v_mov_b32_e32 v87, v3
	v_lshl_add_u64 v[180:181], v[6:7], 0, v[86:87]
	global_store_short_d16_hi v[180:181], v89, off
	v_bfe_u32 v89, v88, 16, 1
	v_add3_u32 v91, v88, v89, s30
	v_or_b32_e32 v88, 0x9000, v2
	v_mov_b32_e32 v89, v3
	v_lshl_add_u64 v[180:181], v[6:7], 0, v[88:89]
	global_store_short_d16_hi v[180:181], v91, off
	v_bfe_u32 v91, v90, 16, 1
	v_add3_u32 v93, v90, v91, s30
	v_or_b32_e32 v90, 0x9800, v2
	v_mov_b32_e32 v91, v3
	v_lshl_add_u64 v[180:181], v[6:7], 0, v[90:91]
	global_store_short_d16_hi v[180:181], v93, off
	v_bfe_u32 v93, v92, 16, 1
	v_add3_u32 v95, v92, v93, s30
	v_or_b32_e32 v92, 0xc000, v2
	v_mov_b32_e32 v93, v3
	v_lshl_add_u64 v[180:181], v[6:7], 0, v[92:93]
	global_store_short_d16_hi v[180:181], v95, off
	v_bfe_u32 v95, v94, 16, 1
	v_add3_u32 v97, v94, v95, s30
	v_or_b32_e32 v94, 0xc800, v2
	v_mov_b32_e32 v95, v3
	v_lshl_add_u64 v[180:181], v[6:7], 0, v[94:95]
	global_store_short_d16_hi v[180:181], v97, off
	v_bfe_u32 v97, v96, 16, 1
	v_add3_u32 v183, v96, v97, s30
	v_or_b32_e32 v96, 0xd000, v2
	v_mov_b32_e32 v97, v3
	v_mul_f32_e32 v178, v165, v178
	v_lshl_add_u64 v[180:181], v[6:7], 0, v[96:97]
	v_mul_f32_e32 v178, v182, v178
	global_store_short_d16_hi v[180:181], v183, off
	v_bfe_u32 v180, v178, 16, 1
	v_or_b32_e32 v2, 0xd800, v2
	v_add3_u32 v178, v178, v180, s30
	v_lshl_add_u64 v[180:181], v[6:7], 0, v[2:3]
	global_store_short_d16_hi v[180:181], v178, off
	global_load_dword v178, v179, s[6:7] offset:128
	v_lshl_add_u64 v[180:181], v[6:7], 0, 64
	s_waitcnt vmcnt(0)
	v_mul_f32_e32 v140, v178, v140
	v_bfe_u32 v182, v140, 16, 1
	v_add3_u32 v140, v140, v182, s30
	global_store_short_d16_hi v[4:5], v140, off offset:64
	v_mul_f32_e32 v140, v135, v142
	v_mul_f32_e32 v140, v178, v140
	v_bfe_u32 v142, v140, 16, 1
	v_add3_u32 v140, v140, v142, s30
	global_store_short_d16_hi v[4:5], v140, off offset:2112
	v_mul_f32_e32 v140, v137, v143
	v_mul_f32_e32 v140, v178, v140
	v_bfe_u32 v142, v140, 16, 1
	v_add3_u32 v140, v140, v142, s30
	v_lshl_add_u64 v[142:143], v[180:181], 0, v[8:9]
	global_store_short_d16_hi v[142:143], v140, off
	v_mul_f32_e32 v140, v141, v146
	v_mul_f32_e32 v140, v178, v140
	v_bfe_u32 v142, v140, 16, 1
	v_add3_u32 v140, v140, v142, s30
	v_lshl_add_u64 v[142:143], v[180:181], 0, v[10:11]
	global_store_short_d16_hi v[142:143], v140, off
	v_mul_f32_e32 v140, v144, v155
	v_mul_f32_e32 v140, v178, v140
	v_bfe_u32 v142, v140, 16, 1
	v_add3_u32 v140, v140, v142, s30
	v_lshl_add_u64 v[142:143], v[180:181], 0, v[12:13]
	global_store_short_d16_hi v[142:143], v140, off
	v_mul_f32_e32 v140, v147, v157
	v_mul_f32_e32 v140, v178, v140
	v_bfe_u32 v142, v140, 16, 1
	v_add3_u32 v140, v140, v142, s30
	v_lshl_add_u64 v[142:143], v[180:181], 0, v[14:15]
	global_store_short_d16_hi v[142:143], v140, off
	v_mul_f32_e32 v140, v148, v158
	v_mul_f32_e32 v140, v178, v140
	v_bfe_u32 v142, v140, 16, 1
	v_add3_u32 v140, v140, v142, s30
	v_lshl_add_u64 v[142:143], v[180:181], 0, v[80:81]
	global_store_short_d16_hi v[142:143], v140, off
	v_mul_f32_e32 v140, v150, v166
	v_mul_f32_e32 v140, v178, v140
	v_bfe_u32 v142, v140, 16, 1
	v_add3_u32 v140, v140, v142, s30
	v_lshl_add_u64 v[142:143], v[180:181], 0, v[82:83]
	global_store_short_d16_hi v[142:143], v140, off
	v_mul_f32_e32 v140, v153, v170
	v_mul_f32_e32 v140, v178, v140
	v_bfe_u32 v142, v140, 16, 1
	v_add3_u32 v140, v140, v142, s30
	v_lshl_add_u64 v[142:143], v[180:181], 0, v[84:85]
	global_store_short_d16_hi v[142:143], v140, off
	v_mul_f32_e32 v140, v156, v171
	v_mul_f32_e32 v140, v178, v140
	v_bfe_u32 v142, v140, 16, 1
	v_add3_u32 v140, v140, v142, s30
	v_lshl_add_u64 v[142:143], v[180:181], 0, v[86:87]
	global_store_short_d16_hi v[142:143], v140, off
	v_mul_f32_e32 v140, v159, v172
	v_mul_f32_e32 v140, v178, v140
	v_bfe_u32 v142, v140, 16, 1
	v_add3_u32 v140, v140, v142, s30
	v_lshl_add_u64 v[142:143], v[180:181], 0, v[88:89]
	global_store_short_d16_hi v[142:143], v140, off
	v_mul_f32_e32 v140, v160, v173
	v_mul_f32_e32 v140, v178, v140
	v_bfe_u32 v142, v140, 16, 1
	v_add3_u32 v140, v140, v142, s30
	v_lshl_add_u64 v[142:143], v[180:181], 0, v[90:91]
	global_store_short_d16_hi v[142:143], v140, off
	v_mul_f32_e32 v140, v161, v174
	v_mul_f32_e32 v140, v178, v140
	v_bfe_u32 v142, v140, 16, 1
	v_add3_u32 v140, v140, v142, s30
	v_lshl_add_u64 v[142:143], v[180:181], 0, v[92:93]
	global_store_short_d16_hi v[142:143], v140, off
	v_mul_f32_e32 v140, v162, v175
	v_mul_f32_e32 v140, v178, v140
	v_bfe_u32 v142, v140, 16, 1
	v_add3_u32 v140, v140, v142, s30
	v_lshl_add_u64 v[142:143], v[180:181], 0, v[94:95]
	global_store_short_d16_hi v[142:143], v140, off
	v_mul_f32_e32 v140, v163, v176
	v_mul_f32_e32 v140, v178, v140
	v_bfe_u32 v142, v140, 16, 1
	v_add3_u32 v140, v140, v142, s30
	v_lshl_add_u64 v[142:143], v[180:181], 0, v[96:97]
	global_store_short_d16_hi v[142:143], v140, off
	v_mul_f32_e32 v140, v165, v177
	v_mul_f32_e32 v140, v178, v140
	v_bfe_u32 v142, v140, 16, 1
	v_add3_u32 v140, v140, v142, s30
	v_lshl_add_u64 v[142:143], v[180:181], 0, v[2:3]
	global_store_short_d16_hi v[142:143], v140, off
	global_load_dword v140, v179, s[6:7] offset:256
	v_lshl_add_u64 v[142:143], v[6:7], 0, s[4:5]
	s_mov_b64 s[4:5], 0xc0
	v_lshl_add_u64 v[6:7], v[6:7], 0, s[4:5]
	s_mov_b64 s[4:5], 0
	s_waitcnt vmcnt(0)
	v_mul_f32_e32 v130, v140, v130
	v_bfe_u32 v146, v130, 16, 1
	v_add3_u32 v130, v130, v146, s30
	global_store_short_d16_hi v[4:5], v130, off offset:128
	v_mul_f32_e32 v130, v135, v131
	v_mul_f32_e32 v130, v140, v130
	v_bfe_u32 v131, v130, 16, 1
	v_add3_u32 v130, v130, v131, s30
	global_store_short_d16_hi v[4:5], v130, off offset:2176
	v_mul_f32_e32 v130, v137, v132
	v_mul_f32_e32 v130, v140, v130
	v_bfe_u32 v131, v130, 16, 1
	v_add3_u32 v132, v130, v131, s30
	v_lshl_add_u64 v[130:131], v[142:143], 0, v[8:9]
	global_store_short_d16_hi v[130:131], v132, off
	v_mul_f32_e32 v130, v141, v133
	v_mul_f32_e32 v130, v140, v130
	v_bfe_u32 v131, v130, 16, 1
	v_add3_u32 v132, v130, v131, s30
	v_lshl_add_u64 v[130:131], v[142:143], 0, v[10:11]
	global_store_short_d16_hi v[130:131], v132, off
	v_mul_f32_e32 v130, v144, v136
	v_mul_f32_e32 v130, v140, v130
	v_bfe_u32 v131, v130, 16, 1
	v_add3_u32 v132, v130, v131, s30
	v_lshl_add_u64 v[130:131], v[142:143], 0, v[12:13]
	global_store_short_d16_hi v[130:131], v132, off
	v_mul_f32_e32 v130, v147, v138
	v_mul_f32_e32 v130, v140, v130
	v_bfe_u32 v131, v130, 16, 1
	v_add3_u32 v132, v130, v131, s30
	v_lshl_add_u64 v[130:131], v[142:143], 0, v[14:15]
	global_store_short_d16_hi v[130:131], v132, off
	v_mul_f32_e32 v130, v148, v139
	v_mul_f32_e32 v130, v140, v130
	v_bfe_u32 v131, v130, 16, 1
	v_add3_u32 v132, v130, v131, s30
	v_lshl_add_u64 v[130:131], v[142:143], 0, v[80:81]
	global_store_short_d16_hi v[130:131], v132, off
	v_mul_f32_e32 v130, v150, v145
	v_mul_f32_e32 v130, v140, v130
	v_bfe_u32 v131, v130, 16, 1
	v_add3_u32 v132, v130, v131, s30
	v_lshl_add_u64 v[130:131], v[142:143], 0, v[82:83]
	global_store_short_d16_hi v[130:131], v132, off
	v_mul_f32_e32 v130, v153, v149
	v_mul_f32_e32 v130, v140, v130
	v_bfe_u32 v131, v130, 16, 1
	v_add3_u32 v132, v130, v131, s30
	v_lshl_add_u64 v[130:131], v[142:143], 0, v[84:85]
	global_store_short_d16_hi v[130:131], v132, off
	v_mul_f32_e32 v130, v156, v151
	v_mul_f32_e32 v130, v140, v130
	v_bfe_u32 v131, v130, 16, 1
	v_add3_u32 v132, v130, v131, s30
	v_lshl_add_u64 v[130:131], v[142:143], 0, v[86:87]
	global_store_short_d16_hi v[130:131], v132, off
	v_mul_f32_e32 v130, v159, v152
	v_mul_f32_e32 v130, v140, v130
	v_bfe_u32 v131, v130, 16, 1
	v_add3_u32 v132, v130, v131, s30
	v_lshl_add_u64 v[130:131], v[142:143], 0, v[88:89]
	global_store_short_d16_hi v[130:131], v132, off
	v_mul_f32_e32 v130, v160, v154
	v_mul_f32_e32 v130, v140, v130
	v_bfe_u32 v131, v130, 16, 1
	v_add3_u32 v132, v130, v131, s30
	v_lshl_add_u64 v[130:131], v[142:143], 0, v[90:91]
	global_store_short_d16_hi v[130:131], v132, off
	v_mul_f32_e32 v130, v161, v164
	v_mul_f32_e32 v130, v140, v130
	v_bfe_u32 v131, v130, 16, 1
	v_add3_u32 v132, v130, v131, s30
	v_lshl_add_u64 v[130:131], v[142:143], 0, v[92:93]
	global_store_short_d16_hi v[130:131], v132, off
	v_mul_f32_e32 v130, v162, v167
	v_mul_f32_e32 v130, v140, v130
	v_bfe_u32 v131, v130, 16, 1
	v_add3_u32 v132, v130, v131, s30
	v_lshl_add_u64 v[130:131], v[142:143], 0, v[94:95]
	global_store_short_d16_hi v[130:131], v132, off
	v_mul_f32_e32 v130, v163, v168
	v_mul_f32_e32 v130, v140, v130
	v_bfe_u32 v131, v130, 16, 1
	v_add3_u32 v132, v130, v131, s30
	v_lshl_add_u64 v[130:131], v[142:143], 0, v[96:97]
	global_store_short_d16_hi v[130:131], v132, off
	v_mul_f32_e32 v130, v165, v169
	v_mul_f32_e32 v130, v140, v130
	v_bfe_u32 v131, v130, 16, 1
	v_add3_u32 v132, v130, v131, s30
	v_lshl_add_u64 v[130:131], v[142:143], 0, v[2:3]
	global_store_short_d16_hi v[130:131], v132, off
	global_load_dword v130, v179, s[6:7] offset:384
	s_waitcnt vmcnt(0)
	v_mul_f32_e32 v114, v130, v114
	v_bfe_u32 v131, v114, 16, 1
	v_add3_u32 v114, v114, v131, s30
	global_store_short_d16_hi v[4:5], v114, off offset:192
	v_mul_f32_e32 v114, v135, v115
	v_mul_f32_e32 v114, v130, v114
	v_bfe_u32 v115, v114, 16, 1
	v_add3_u32 v114, v114, v115, s30
	global_store_short_d16_hi v[4:5], v114, off offset:2240
	v_mul_f32_e32 v4, v137, v116
	v_mul_f32_e32 v4, v130, v4
	v_bfe_u32 v5, v4, 16, 1
	v_add3_u32 v114, v4, v5, s30
	v_lshl_add_u64 v[4:5], v[6:7], 0, v[8:9]
	global_store_short_d16_hi v[4:5], v114, off
	v_mul_f32_e32 v4, v141, v117
	v_mul_f32_e32 v4, v130, v4
	v_bfe_u32 v5, v4, 16, 1
	v_add3_u32 v8, v4, v5, s30
	v_lshl_add_u64 v[4:5], v[6:7], 0, v[10:11]
	global_store_short_d16_hi v[4:5], v8, off
	v_mul_f32_e32 v4, v144, v119
	v_mul_f32_e32 v4, v130, v4
	v_bfe_u32 v5, v4, 16, 1
	v_add3_u32 v8, v4, v5, s30
	v_lshl_add_u64 v[4:5], v[6:7], 0, v[12:13]
	global_store_short_d16_hi v[4:5], v8, off
	v_mul_f32_e32 v4, v147, v118
	v_mul_f32_e32 v4, v130, v4
	v_bfe_u32 v5, v4, 16, 1
	v_add3_u32 v8, v4, v5, s30
	v_lshl_add_u64 v[4:5], v[6:7], 0, v[14:15]
	global_store_short_d16_hi v[4:5], v8, off
	v_mul_f32_e32 v4, v148, v120
	v_mul_f32_e32 v4, v130, v4
	v_bfe_u32 v5, v4, 16, 1
	v_add3_u32 v8, v4, v5, s30
	v_lshl_add_u64 v[4:5], v[6:7], 0, v[80:81]
	global_store_short_d16_hi v[4:5], v8, off
	v_mul_f32_e32 v4, v150, v121
	v_mul_f32_e32 v4, v130, v4
	v_bfe_u32 v5, v4, 16, 1
	v_add3_u32 v8, v4, v5, s30
	v_lshl_add_u64 v[4:5], v[6:7], 0, v[82:83]
	global_store_short_d16_hi v[4:5], v8, off
	v_mul_f32_e32 v4, v153, v123
	v_mul_f32_e32 v4, v130, v4
	v_bfe_u32 v5, v4, 16, 1
	v_add3_u32 v8, v4, v5, s30
	v_lshl_add_u64 v[4:5], v[6:7], 0, v[84:85]
	global_store_short_d16_hi v[4:5], v8, off
	v_mul_f32_e32 v4, v156, v122
	v_mul_f32_e32 v4, v130, v4
	v_bfe_u32 v5, v4, 16, 1
	v_add3_u32 v8, v4, v5, s30
	v_lshl_add_u64 v[4:5], v[6:7], 0, v[86:87]
	global_store_short_d16_hi v[4:5], v8, off
	v_mul_f32_e32 v4, v159, v124
	v_mul_f32_e32 v4, v130, v4
	v_bfe_u32 v5, v4, 16, 1
	v_add3_u32 v8, v4, v5, s30
	v_lshl_add_u64 v[4:5], v[6:7], 0, v[88:89]
	global_store_short_d16_hi v[4:5], v8, off
	v_mul_f32_e32 v4, v160, v125
	v_mul_f32_e32 v4, v130, v4
	v_bfe_u32 v5, v4, 16, 1
	v_add3_u32 v8, v4, v5, s30
	v_lshl_add_u64 v[4:5], v[6:7], 0, v[90:91]
	global_store_short_d16_hi v[4:5], v8, off
	v_mul_f32_e32 v4, v161, v127
	v_mul_f32_e32 v4, v130, v4
	v_bfe_u32 v5, v4, 16, 1
	v_add3_u32 v8, v4, v5, s30
	v_lshl_add_u64 v[4:5], v[6:7], 0, v[92:93]
	global_store_short_d16_hi v[4:5], v8, off
	v_mul_f32_e32 v4, v162, v126
	v_mul_f32_e32 v4, v130, v4
	v_bfe_u32 v5, v4, 16, 1
	v_add3_u32 v8, v4, v5, s30
	v_lshl_add_u64 v[4:5], v[6:7], 0, v[94:95]
	global_store_short_d16_hi v[4:5], v8, off
	v_mul_f32_e32 v4, v163, v128
	v_mul_f32_e32 v4, v130, v4
	v_bfe_u32 v5, v4, 16, 1
	v_add3_u32 v8, v4, v5, s30
	v_lshl_add_u64 v[4:5], v[6:7], 0, v[96:97]
	global_store_short_d16_hi v[4:5], v8, off
	v_mul_f32_e32 v4, v165, v129
	v_mul_f32_e32 v4, v130, v4
	v_bfe_u32 v5, v4, 16, 1
	v_add3_u32 v8, v4, v5, s30
	v_lshl_add_u64 v[4:5], v[6:7], 0, v[2:3]
	global_store_short_d16_hi v[4:5], v8, off
